# lever 2: prologue x->fp16 loop unrolled x4 (eight 16-byte loads in flight per lane before the first conversion, counted waits)
# baseline (speedup 1.0000x reference)
; __device__ __forceinline__ void p_prologue(const Params& P, LAS unsigned char* lds) {
;     ...
;     { h16* Hh = (h16*)(P.ws + WS_X16); const size_t nvec = (size_t)M_TOK * DM / 8;
;       for (size_t v = (size_t)c * NT + tid; v < nvec; v += (size_t)G * NT) {
;           const f32x4 a = __builtin_nontemporal_load((const f32x4*)P.x + 2 * v), b = __builtin_nontemporal_load((const f32x4*)P.x + 2 * v + 1);
;           u32x4 w; w.x = pk2h(a[0], a[1]); w.y = pk2h(a[2], a[3]); w.z = pk2h(b[0], b[1]); w.w = pk2h(b[2], b[3]); ((u32x4*)Hh)[v] = w; } }
.LBB0_23:
	global_load_dwordx4 v[8:11], v[6:7], off offset:-16 nt
	global_load_dwordx4 v[12:15], v[6:7], off nt
	v_lshl_add_u64 v[6:7], v[6:7], 0, s[10:11]
	global_load_dwordx4 v[16:19], v[6:7], off offset:-16 nt
	global_load_dwordx4 v[20:23], v[6:7], off nt
	v_lshl_add_u64 v[6:7], v[6:7], 0, s[10:11]
	global_load_dwordx4 v[24:27], v[6:7], off offset:-16 nt
	global_load_dwordx4 v[28:31], v[6:7], off nt
	v_lshl_add_u64 v[6:7], v[6:7], 0, s[10:11]
	global_load_dwordx4 v[32:35], v[6:7], off offset:-16 nt
	global_load_dwordx4 v[36:39], v[6:7], off nt
	v_lshl_add_u64 v[6:7], v[6:7], 0, s[10:11]
	v_lshl_add_u64 v[2:3], v[2:3], 0, s[6:7]
	v_lshl_add_u64 v[2:3], v[2:3], 0, s[6:7]
	v_lshl_add_u64 v[2:3], v[2:3], 0, s[6:7]
	v_lshl_add_u64 v[2:3], v[2:3], 0, s[6:7]
	v_cmp_lt_u64_e32 vcc, s[14:15], v[2:3]
	s_or_b64 s[12:13], vcc, s[12:13]
	s_waitcnt vmcnt(7)
	v_cvt_pk_f16_f32 v8, v8, v9
	v_cvt_pk_f16_f32 v9, v10, v11
	s_waitcnt vmcnt(6)
	v_cvt_pk_f16_f32 v10, v12, v13
	v_cvt_pk_f16_f32 v11, v14, v15
	global_store_dwordx4 v[4:5], v[8:11], off
	v_lshl_add_u64 v[4:5], v[4:5], 0, s[8:9]
	s_waitcnt vmcnt(6)
	v_cvt_pk_f16_f32 v16, v16, v17
	v_cvt_pk_f16_f32 v17, v18, v19
	s_waitcnt vmcnt(5)
	v_cvt_pk_f16_f32 v18, v20, v21
	v_cvt_pk_f16_f32 v19, v22, v23
	global_store_dwordx4 v[4:5], v[16:19], off
	v_lshl_add_u64 v[4:5], v[4:5], 0, s[8:9]
	s_waitcnt vmcnt(5)
	v_cvt_pk_f16_f32 v24, v24, v25
	v_cvt_pk_f16_f32 v25, v26, v27
	s_waitcnt vmcnt(4)
	v_cvt_pk_f16_f32 v26, v28, v29
	v_cvt_pk_f16_f32 v27, v30, v31
	global_store_dwordx4 v[4:5], v[24:27], off
	v_lshl_add_u64 v[4:5], v[4:5], 0, s[8:9]
	s_waitcnt vmcnt(4)
	v_cvt_pk_f16_f32 v32, v32, v33
	v_cvt_pk_f16_f32 v33, v34, v35
	s_waitcnt vmcnt(3)
	v_cvt_pk_f16_f32 v34, v36, v37
	v_cvt_pk_f16_f32 v35, v38, v39
	global_store_dwordx4 v[4:5], v[32:35], off
	v_lshl_add_u64 v[4:5], v[4:5], 0, s[8:9]
	s_andn2_b64 exec, exec, s[12:13]
	s_cbranch_execnz .LBB0_23
